# GEMM K-loop heads (in-proj and out-proj) aligned to 64 bytes
# speedup vs baseline: 1.0052x; 1.0052x over previous
.LBB0_244:
	s_ashr_i32 s53, s52, 31
	s_lshl_b64 s[12:13], s[52:53], 20
	v_readlane_b32 s11, v243, 37
	s_add_u32 s54, s11, s12
	v_readlane_b32 s11, v243, 38
	s_addc_u32 s55, s11, s13
	s_and_b64 s[12:13], s[40:41], exec
	s_cselect_b32 s11, s55, s43
	s_cselect_b32 s53, s54, s42
	s_ashr_i32 s51, s50, 31
	s_lshl_b64 s[12:13], s[50:51], 20
	s_add_u32 s58, s91, s12
	s_addc_u32 s59, s97, s13
	s_and_b64 s[12:13], s[40:41], exec
	s_cselect_b32 s51, s59, s73
	s_cselect_b32 vcc_lo, s58, s72
	s_add_u32 s42, s42, 0x80080
	s_addc_u32 s43, s43, 0
	s_add_u32 vcc_hi, s72, 0x100
	v_mov_b32_e32 v0, 0
	s_addc_u32 s12, s73, 0
	s_mov_b32 s13, -2
	v_mov_b32_e32 v1, v0
	v_mov_b32_e32 v2, v0
	v_mov_b32_e32 v3, v0
	v_mov_b32_e32 v4, v0
	v_mov_b32_e32 v5, v0
	v_mov_b32_e32 v6, v0
	v_mov_b32_e32 v7, v0
	v_mov_b32_e32 v16, v0
	v_mov_b32_e32 v17, v0
	v_mov_b32_e32 v18, v0
	v_mov_b32_e32 v19, v0
	v_mov_b32_e32 v20, v0
	v_mov_b32_e32 v21, v0
	v_mov_b32_e32 v22, v0
	v_mov_b32_e32 v23, v0
	s_waitcnt vmcnt(0)
	v_mov_b32_e32 v32, v0
	v_mov_b32_e32 v33, v0
	v_mov_b32_e32 v34, v0
	v_mov_b32_e32 v35, v0
	v_mov_b32_e32 v36, v0
	v_mov_b32_e32 v37, v0
	v_mov_b32_e32 v38, v0
	v_mov_b32_e32 v39, v0
	v_mov_b32_e32 v48, v0
	v_mov_b32_e32 v49, v0
	v_mov_b32_e32 v50, v0
	v_mov_b32_e32 v51, v0
	v_mov_b32_e32 v52, v0
	v_mov_b32_e32 v53, v0
	v_mov_b32_e32 v54, v0
	v_mov_b32_e32 v55, v0
	v_mov_b32_e32 v8, v0
	v_mov_b32_e32 v9, v0
	v_mov_b32_e32 v10, v0
	v_mov_b32_e32 v11, v0
	v_mov_b32_e32 v12, v0
	v_mov_b32_e32 v13, v0
	v_mov_b32_e32 v14, v0
	v_mov_b32_e32 v15, v0
	v_mov_b32_e32 v24, v0
	v_mov_b32_e32 v25, v0
	v_mov_b32_e32 v26, v0
	v_mov_b32_e32 v27, v0
	v_mov_b32_e32 v28, v0
	v_mov_b32_e32 v29, v0
	v_mov_b32_e32 v30, v0
	v_mov_b32_e32 v31, v0
	v_mov_b32_e32 v40, v0
	v_mov_b32_e32 v41, v0
	v_mov_b32_e32 v42, v0
	v_mov_b32_e32 v43, v0
	v_mov_b32_e32 v44, v0
	v_mov_b32_e32 v45, v0
	v_mov_b32_e32 v46, v0
	v_mov_b32_e32 v47, v0
	v_mov_b32_e32 v72, v0
	v_mov_b32_e32 v73, v0
	v_mov_b32_e32 v74, v0
	v_mov_b32_e32 v75, v0
	v_mov_b32_e32 v76, v0
	v_mov_b32_e32 v77, v0
	v_mov_b32_e32 v78, v0
	v_mov_b32_e32 v79, v0
	v_mov_b32_e32 v80, v0
	v_mov_b32_e32 v81, v0
	v_mov_b32_e32 v82, v0
	v_mov_b32_e32 v83, v0
	v_mov_b32_e32 v84, v0
	v_mov_b32_e32 v85, v0
	v_mov_b32_e32 v86, v0
	v_mov_b32_e32 v87, v0
	v_mov_b32_e32 v96, v0
	v_mov_b32_e32 v97, v0
	v_mov_b32_e32 v98, v0
	v_mov_b32_e32 v99, v0
	v_mov_b32_e32 v100, v0
	v_mov_b32_e32 v101, v0
	v_mov_b32_e32 v102, v0
	v_mov_b32_e32 v103, v0
	v_mov_b32_e32 v112, v0
	v_mov_b32_e32 v113, v0
	v_mov_b32_e32 v114, v0
	v_mov_b32_e32 v115, v0
	v_mov_b32_e32 v116, v0
	v_mov_b32_e32 v117, v0
	v_mov_b32_e32 v118, v0
	v_mov_b32_e32 v119, v0
	v_mov_b32_e32 v128, v0
	v_mov_b32_e32 v129, v0
	v_mov_b32_e32 v130, v0
	v_mov_b32_e32 v131, v0
	v_mov_b32_e32 v132, v0
	v_mov_b32_e32 v133, v0
	v_mov_b32_e32 v134, v0
	v_mov_b32_e32 v135, v0
	v_mov_b32_e32 v88, v0
	v_mov_b32_e32 v89, v0
	v_mov_b32_e32 v90, v0
	v_mov_b32_e32 v91, v0
	v_mov_b32_e32 v92, v0
	v_mov_b32_e32 v93, v0
	v_mov_b32_e32 v94, v0
	v_mov_b32_e32 v95, v0
	v_mov_b32_e32 v104, v0
	v_mov_b32_e32 v105, v0
	v_mov_b32_e32 v106, v0
	v_mov_b32_e32 v107, v0
	v_mov_b32_e32 v108, v0
	v_mov_b32_e32 v109, v0
	v_mov_b32_e32 v110, v0
	v_mov_b32_e32 v111, v0
	v_mov_b32_e32 v120, v0
	v_mov_b32_e32 v121, v0
	v_mov_b32_e32 v122, v0
	v_mov_b32_e32 v123, v0
	v_mov_b32_e32 v124, v0
	v_mov_b32_e32 v125, v0
	v_mov_b32_e32 v126, v0
	v_mov_b32_e32 v127, v0
	v_mov_b32_e32 v136, v0
	v_mov_b32_e32 v137, v0
	v_mov_b32_e32 v138, v0
	v_mov_b32_e32 v139, v0
	v_mov_b32_e32 v140, v0
	v_mov_b32_e32 v141, v0
	v_mov_b32_e32 v142, v0
	v_mov_b32_e32 v143, v0
	.p2alignl 6, 3212836864

.LBB0_712:
	s_ashr_i32 s51, s50, 31
	s_lshl_b64 s[10:11], s[50:51], 20
	v_readlane_b32 s12, v243, 48
	s_add_u32 s52, s12, s10
	v_readlane_b32 s10, v243, 49
	s_addc_u32 s53, s10, s11
	s_and_b64 s[10:11], s[40:41], exec
	s_cselect_b32 s10, s53, s59
	s_cselect_b32 s11, s52, s58
	s_ashr_i32 s49, s48, 31
	s_lshl_b64 s[12:13], s[48:49], 20
	s_add_u32 s54, s5, s12
	s_addc_u32 s55, s6, s13
	s_and_b64 s[12:13], s[40:41], exec
	s_cselect_b32 s49, s55, s73
	s_cselect_b32 s51, s54, s72
	s_add_u32 s58, s58, 0x80080
	s_addc_u32 s59, s59, 0
	s_add_u32 s97, s72, 0x100
	v_mov_b32_e32 v0, 0
	s_addc_u32 s12, s73, 0
	s_mov_b32 s13, -2
	v_mov_b32_e32 v1, v0
	v_mov_b32_e32 v2, v0
	v_mov_b32_e32 v3, v0
	v_mov_b32_e32 v4, v0
	v_mov_b32_e32 v5, v0
	v_mov_b32_e32 v6, v0
	v_mov_b32_e32 v7, v0
	v_mov_b32_e32 v12, v0
	v_mov_b32_e32 v13, v0
	v_mov_b32_e32 v14, v0
	v_mov_b32_e32 v15, v0
	v_mov_b32_e32 v20, v0
	v_mov_b32_e32 v21, v0
	v_mov_b32_e32 v22, v0
	v_mov_b32_e32 v23, v0
	v_mov_b32_e32 v28, v0
	v_mov_b32_e32 v29, v0
	v_mov_b32_e32 v30, v0
	v_mov_b32_e32 v31, v0
	s_waitcnt vmcnt(0)
	v_mov_b32_e32 v36, v0
	v_mov_b32_e32 v37, v0
	v_mov_b32_e32 v38, v0
	v_mov_b32_e32 v39, v0
	v_mov_b32_e32 v44, v0
	v_mov_b32_e32 v45, v0
	v_mov_b32_e32 v46, v0
	v_mov_b32_e32 v47, v0
	v_mov_b32_e32 v52, v0
	v_mov_b32_e32 v53, v0
	v_mov_b32_e32 v54, v0
	v_mov_b32_e32 v55, v0
	v_mov_b32_e32 v8, v0
	v_mov_b32_e32 v9, v0
	v_mov_b32_e32 v10, v0
	v_mov_b32_e32 v11, v0
	v_mov_b32_e32 v16, v0
	v_mov_b32_e32 v17, v0
	v_mov_b32_e32 v18, v0
	v_mov_b32_e32 v19, v0
	v_mov_b32_e32 v24, v0
	v_mov_b32_e32 v25, v0
	v_mov_b32_e32 v26, v0
	v_mov_b32_e32 v27, v0
	v_mov_b32_e32 v32, v0
	v_mov_b32_e32 v33, v0
	v_mov_b32_e32 v34, v0
	v_mov_b32_e32 v35, v0
	v_mov_b32_e32 v40, v0
	v_mov_b32_e32 v41, v0
	v_mov_b32_e32 v42, v0
	v_mov_b32_e32 v43, v0
	v_mov_b32_e32 v48, v0
	v_mov_b32_e32 v49, v0
	v_mov_b32_e32 v50, v0
	v_mov_b32_e32 v51, v0
	v_mov_b32_e32 v56, v0
	v_mov_b32_e32 v57, v0
	v_mov_b32_e32 v58, v0
	v_mov_b32_e32 v59, v0
	v_mov_b32_e32 v60, v0
	v_mov_b32_e32 v61, v0
	v_mov_b32_e32 v62, v0
	v_mov_b32_e32 v63, v0
	v_mov_b32_e32 v64, v0
	v_mov_b32_e32 v65, v0
	v_mov_b32_e32 v66, v0
	v_mov_b32_e32 v67, v0
	v_mov_b32_e32 v68, v0
	v_mov_b32_e32 v69, v0
	v_mov_b32_e32 v70, v0
	v_mov_b32_e32 v71, v0
	v_mov_b32_e32 v80, v0
	v_mov_b32_e32 v81, v0
	v_mov_b32_e32 v82, v0
	v_mov_b32_e32 v83, v0
	v_mov_b32_e32 v84, v0
	v_mov_b32_e32 v85, v0
	v_mov_b32_e32 v86, v0
	v_mov_b32_e32 v87, v0
	v_mov_b32_e32 v112, v0
	v_mov_b32_e32 v113, v0
	v_mov_b32_e32 v114, v0
	v_mov_b32_e32 v115, v0
	v_mov_b32_e32 v116, v0
	v_mov_b32_e32 v117, v0
	v_mov_b32_e32 v118, v0
	v_mov_b32_e32 v119, v0
	v_mov_b32_e32 v128, v0
	v_mov_b32_e32 v129, v0
	v_mov_b32_e32 v130, v0
	v_mov_b32_e32 v131, v0
	v_mov_b32_e32 v132, v0
	v_mov_b32_e32 v133, v0
	v_mov_b32_e32 v134, v0
	v_mov_b32_e32 v135, v0
	v_mov_b32_e32 v72, v0
	v_mov_b32_e32 v73, v0
	v_mov_b32_e32 v74, v0
	v_mov_b32_e32 v75, v0
	v_mov_b32_e32 v76, v0
	v_mov_b32_e32 v77, v0
	v_mov_b32_e32 v78, v0
	v_mov_b32_e32 v79, v0
	v_mov_b32_e32 v88, v0
	v_mov_b32_e32 v89, v0
	v_mov_b32_e32 v90, v0
	v_mov_b32_e32 v91, v0
	v_mov_b32_e32 v92, v0
	v_mov_b32_e32 v93, v0
	v_mov_b32_e32 v94, v0
	v_mov_b32_e32 v95, v0
	v_mov_b32_e32 v120, v0
	v_mov_b32_e32 v121, v0
	v_mov_b32_e32 v122, v0
	v_mov_b32_e32 v123, v0
	v_mov_b32_e32 v124, v0
	v_mov_b32_e32 v125, v0
	v_mov_b32_e32 v126, v0
	v_mov_b32_e32 v127, v0
	v_mov_b32_e32 v136, v0
	v_mov_b32_e32 v137, v0
	v_mov_b32_e32 v138, v0
	v_mov_b32_e32 v139, v0
	v_mov_b32_e32 v140, v0
	v_mov_b32_e32 v141, v0
	v_mov_b32_e32 v142, v0
	v_mov_b32_e32 v143, v0
	.p2alignl 6, 3212836864
